# P5/P6: quarter-mode test moved from the full-tile K-loop head (every iteration) to the loop preheader (once per unit)
# baseline (speedup 1.0000x reference)
.LBB0_1130:
	s_cmp_lt_i32 s76, 1
	s_cselect_b64 s[26:27], -1, 0
	s_add_u32 s34, s34, 0x80080
	s_addc_u32 s35, s35, 0
	v_mov_b32_e32 v2, v0
	v_mov_b32_e32 v3, v0
	s_add_u32 s18, s2, 0x100
	v_mov_b32_e32 v1, v0
	v_mov_b32_e32 v84, 0
	v_mov_b64_e32 v[6:7], v[2:3]
	v_mov_b64_e32 v[10:11], v[2:3]
	v_mov_b64_e32 v[22:23], v[2:3]
	v_mov_b64_e32 v[26:27], v[2:3]
	v_mov_b64_e32 v[38:39], v[2:3]
	v_mov_b64_e32 v[42:43], v[2:3]
	v_mov_b64_e32 v[54:55], v[2:3]
	v_mov_b64_e32 v[58:59], v[2:3]
	v_mov_b64_e32 v[14:15], v[2:3]
	v_mov_b64_e32 v[18:19], v[2:3]
	v_mov_b64_e32 v[30:31], v[2:3]
	v_mov_b64_e32 v[34:35], v[2:3]
	v_mov_b64_e32 v[46:47], v[2:3]
	v_mov_b64_e32 v[50:51], v[2:3]
	v_mov_b64_e32 v[62:63], v[2:3]
	v_mov_b64_e32 v[66:67], v[2:3]
	v_mov_b64_e32 v[70:71], v[2:3]
	v_mov_b64_e32 v[74:75], v[2:3]
	v_mov_b64_e32 v[78:79], v[2:3]
	v_mov_b64_e32 v[82:83], v[2:3]
	v_mov_b64_e32 v[94:95], v[2:3]
	v_mov_b64_e32 v[98:99], v[2:3]
	v_mov_b64_e32 v[110:111], v[2:3]
	v_mov_b64_e32 v[114:115], v[2:3]
	s_addc_u32 s41, s3, 0
	s_mov_b32 s77, -2
	v_cndmask_b32_e64 v217, 0, 1, s[26:27]
	v_mov_b64_e32 v[4:5], v[0:1]
	v_mov_b64_e32 v[8:9], v[0:1]
	v_mov_b64_e32 v[20:21], v[0:1]
	v_mov_b64_e32 v[24:25], v[0:1]
	v_mov_b64_e32 v[36:37], v[0:1]
	v_mov_b64_e32 v[40:41], v[0:1]
	v_mov_b64_e32 v[52:53], v[0:1]
	v_mov_b64_e32 v[56:57], v[0:1]
	v_mov_b64_e32 v[12:13], v[0:1]
	v_mov_b64_e32 v[16:17], v[0:1]
	v_mov_b64_e32 v[28:29], v[0:1]
	v_mov_b64_e32 v[32:33], v[0:1]
	v_mov_b64_e32 v[44:45], v[0:1]
	v_mov_b64_e32 v[48:49], v[0:1]
	v_mov_b64_e32 v[60:61], v[0:1]
	v_mov_b64_e32 v[64:65], v[0:1]
	v_mov_b64_e32 v[68:69], v[0:1]
	v_mov_b64_e32 v[72:73], v[0:1]
	v_mov_b64_e32 v[76:77], v[0:1]
	v_mov_b64_e32 v[80:81], v[0:1]
	v_mov_b64_e32 v[92:93], v[0:1]
	v_mov_b64_e32 v[96:97], v[0:1]
	v_mov_b64_e32 v[108:109], v[0:1]
	v_mov_b64_e32 v[112:113], v[0:1]
	v_mov_b32_e32 v85, v84
	v_mov_b32_e32 v86, v84
	v_mov_b32_e32 v87, v84
	v_mov_b32_e32 v88, v84
	v_mov_b32_e32 v89, v84
	v_mov_b32_e32 v90, v84
	v_mov_b32_e32 v91, v84
	v_mov_b32_e32 v100, v84
	v_mov_b32_e32 v101, v84
	v_mov_b32_e32 v102, v84
	v_mov_b32_e32 v103, v84
	v_mov_b32_e32 v104, v84
	v_mov_b32_e32 v105, v84
	v_mov_b32_e32 v106, v84
	v_mov_b32_e32 v107, v84
	v_mov_b32_e32 v116, v84
	v_mov_b32_e32 v117, v84
	v_mov_b32_e32 v118, v84
	v_mov_b32_e32 v119, v84
	v_mov_b32_e32 v120, v84
	v_mov_b32_e32 v121, v84
	v_mov_b32_e32 v122, v84
	v_mov_b32_e32 v123, v84
	v_mov_b32_e32 v124, v84
	v_mov_b32_e32 v125, v84
	v_mov_b32_e32 v126, v84
	v_mov_b32_e32 v127, v84
	v_mov_b32_e32 v128, v84
	v_mov_b32_e32 v129, v84
	v_mov_b32_e32 v130, v84
	v_mov_b32_e32 v131, v84
	s_andn2_b64 vcc, exec, s[26:27]
	s_cbranch_vccnz .Lq5_entry
	s_branch .LBB0_1132
	s_nop 0
	s_nop 0
	s_nop 0
	s_nop 0
	s_nop 0
	s_nop 0
	s_nop 0
	s_nop 0
	s_nop 0
	s_nop 0
	s_nop 0

.LBB0_1132:
	ds_read_b128 v[148:151], v214
	ds_read_b128 v[152:155], v214 offset:1024
	ds_read_b128 v[156:159], v214 offset:2048
	ds_read_b128 v[160:163], v214 offset:3072
	ds_read_b128 v[132:135], v215
	ds_read_b128 v[136:139], v215 offset:1024
	ds_read_b128 v[140:143], v215 offset:2048
	ds_read_b128 v[144:147], v215 offset:3072
	v_lshl_add_u64 v[2:3], s[34:35], 0, v[200:201]
	s_add_i32 m0, s48, 0xc000
	s_waitcnt lgkmcnt(0)
	ds_read_b128 v[188:191], v216
	ds_read_b128 v[192:195], v216 offset:1024
	ds_read_b128 v[180:183], v216 offset:2048
	ds_read_b128 v[184:187], v216 offset:3072
	ds_read_b128 v[172:175], v216 offset:4096
	ds_read_b128 v[176:179], v216 offset:5120
	ds_read_b128 v[164:167], v216 offset:6144
	ds_read_b128 v[168:171], v216 offset:7168
	global_load_lds_dwordx4 v[2:3], off
	v_lshl_add_u64 v[2:3], s[34:35], 0, v[202:203]
	s_add_i32 m0, s48, 0xe000
	s_nop 0
	global_load_lds_dwordx4 v[2:3], off
	s_waitcnt vmcnt(8)
	s_waitcnt lgkmcnt(0)
	s_barrier
	s_setprio 1
	s_waitcnt lgkmcnt(0)
	v_mfma_f32_16x16x32_bf16 v[128:131], v[148:151], v[188:191], v[128:131]
	v_mfma_f32_16x16x32_bf16 v[124:127], v[156:159], v[188:191], v[124:127]
	v_mfma_f32_16x16x32_bf16 v[120:123], v[148:151], v[180:183], v[120:123]
	v_mfma_f32_16x16x32_bf16 v[116:119], v[156:159], v[180:183], v[116:119]
	v_mfma_f32_16x16x32_bf16 v[104:107], v[148:151], v[172:175], v[104:107]
	v_mfma_f32_16x16x32_bf16 v[100:103], v[156:159], v[172:175], v[100:103]
	v_mfma_f32_16x16x32_bf16 v[88:91], v[148:151], v[164:167], v[88:91]
	v_mfma_f32_16x16x32_bf16 v[84:87], v[156:159], v[164:167], v[84:87]
	v_mfma_f32_16x16x32_bf16 v[128:131], v[152:155], v[192:195], v[128:131]
	v_mfma_f32_16x16x32_bf16 v[124:127], v[160:163], v[192:195], v[124:127]
	v_mfma_f32_16x16x32_bf16 v[120:123], v[152:155], v[184:187], v[120:123]
	v_mfma_f32_16x16x32_bf16 v[116:119], v[160:163], v[184:187], v[116:119]
	v_mfma_f32_16x16x32_bf16 v[104:107], v[152:155], v[176:179], v[104:107]
	v_mfma_f32_16x16x32_bf16 v[100:103], v[160:163], v[176:179], v[100:103]
	v_mfma_f32_16x16x32_bf16 v[88:91], v[152:155], v[168:171], v[88:91]
	v_mfma_f32_16x16x32_bf16 v[84:87], v[160:163], v[168:171], v[84:87]
	s_setprio 0
	v_cmp_ne_u32_e64 s[2:3], 1, v217
	s_andn2_b64 vcc, exec, s[26:27]
	s_setprio 1
	v_mfma_f32_16x16x32_bf16 v[112:115], v[132:135], v[188:191], v[112:115]
	v_mfma_f32_16x16x32_bf16 v[108:111], v[140:143], v[188:191], v[108:111]
	v_mfma_f32_16x16x32_bf16 v[96:99], v[132:135], v[180:183], v[96:99]
	v_mfma_f32_16x16x32_bf16 v[92:95], v[140:143], v[180:183], v[92:95]
	v_mfma_f32_16x16x32_bf16 v[80:83], v[132:135], v[172:175], v[80:83]
	v_mfma_f32_16x16x32_bf16 v[76:79], v[140:143], v[172:175], v[76:79]
	v_mfma_f32_16x16x32_bf16 v[72:75], v[132:135], v[164:167], v[72:75]
	v_mfma_f32_16x16x32_bf16 v[68:71], v[140:143], v[164:167], v[68:71]
	v_mfma_f32_16x16x32_bf16 v[112:115], v[136:139], v[192:195], v[112:115]
	v_mfma_f32_16x16x32_bf16 v[108:111], v[144:147], v[192:195], v[108:111]
	v_mfma_f32_16x16x32_bf16 v[96:99], v[136:139], v[184:187], v[96:99]
	v_mfma_f32_16x16x32_bf16 v[92:95], v[144:147], v[184:187], v[92:95]
	v_mfma_f32_16x16x32_bf16 v[80:83], v[136:139], v[176:179], v[80:83]
	v_mfma_f32_16x16x32_bf16 v[76:79], v[144:147], v[176:179], v[76:79]
	v_mfma_f32_16x16x32_bf16 v[72:75], v[136:139], v[168:171], v[72:75]
	v_mfma_f32_16x16x32_bf16 v[68:71], v[144:147], v[168:171], v[68:71]
	s_setprio 0

.Lq5_entry:
	v_mov_b32_e32 v4, 0
	v_mov_b32_e32 v5, 0
	v_mov_b32_e32 v6, 0
	v_mov_b32_e32 v7, 0
	v_mov_b32_e32 v8, 0
	v_mov_b32_e32 v9, 0
	v_mov_b32_e32 v10, 0
	v_mov_b32_e32 v11, 0
	v_mov_b32_e32 v12, 0
	v_mov_b32_e32 v13, 0
	v_mov_b32_e32 v14, 0
	v_mov_b32_e32 v15, 0
	v_mov_b32_e32 v16, 0
	v_mov_b32_e32 v17, 0
	v_mov_b32_e32 v18, 0
	v_mov_b32_e32 v19, 0
	v_mov_b32_e32 v20, 0
	v_mov_b32_e32 v21, 0
	v_mov_b32_e32 v22, 0
	v_mov_b32_e32 v23, 0
	v_mov_b32_e32 v24, 0
	v_mov_b32_e32 v25, 0
	v_mov_b32_e32 v26, 0
	v_mov_b32_e32 v27, 0
	v_mov_b32_e32 v28, 0
	v_mov_b32_e32 v29, 0
	v_mov_b32_e32 v30, 0
	v_mov_b32_e32 v31, 0
	v_mov_b32_e32 v32, 0
	v_mov_b32_e32 v33, 0
	v_mov_b32_e32 v34, 0
	v_mov_b32_e32 v35, 0
	v_mov_b32_e32 v36, 0
	v_mov_b32_e32 v37, 0
	v_mov_b32_e32 v38, 0
	v_mov_b32_e32 v39, 0
	v_mov_b32_e32 v40, 0
	v_mov_b32_e32 v41, 0
	v_mov_b32_e32 v42, 0
	v_mov_b32_e32 v43, 0
	v_mov_b32_e32 v44, 0
	v_mov_b32_e32 v45, 0
	v_mov_b32_e32 v46, 0
	v_mov_b32_e32 v47, 0
	v_mov_b32_e32 v48, 0
	v_mov_b32_e32 v49, 0
	v_mov_b32_e32 v50, 0
	v_mov_b32_e32 v51, 0
	v_cmp_ne_u32_e64 s[2:3], 1, v217
	s_andn2_b64 vcc, exec, s[26:27]
	s_add_u32 s56, s34, 0xfff80080
	s_addc_u32 s57, s35, -1
	s_cmp_eq_u32 s77, 12
	s_cselect_b32 s59, s39, s57
	s_cselect_b32 s58, s38, s56
	s_cselect_b32 s57, s47, s41
	s_cselect_b32 s56, s46, s18
	s_mov_b32 m0, s51
	v_lshl_add_u64 v[2:3], s[56:57], 0, v[198:199]
	s_add_u32 s78, s56, 0x80000
	global_load_lds_dwordx4 v[2:3], off
	v_lshl_add_u64 v[204:205], s[56:57], 0, v[196:197]
	s_mov_b32 m0, s60
	s_addc_u32 s79, s57, 0
	global_load_lds_dwordx4 v[204:205], off
	v_lshl_add_u64 v[206:207], s[78:79], 0, v[198:199]
	s_mov_b32 m0, s66
	v_lshl_add_u64 v[208:209], s[58:59], 0, v[196:197]
	v_lshl_add_u64 v[206:207], s[78:79], 0, v[196:197]
	s_mov_b32 m0, s67
	s_and_b64 vcc, exec, s[2:3]
	v_lshl_add_u64 v[206:207], s[58:59], 0, v[198:199]
	s_mov_b32 m0, s62
	s_nop 0
	global_load_lds_dwordx4 v[206:207], off
	s_mov_b32 m0, s63
	s_nop 0
	global_load_lds_dwordx4 v[208:209], off
	s_and_b64 vcc, exec, s[2:3]
	s_mov_b32 m0, s70
	v_lshl_add_u64 v[2:3], v[2:3], 0, s[16:17]
	s_add_u32 s56, s56, 0x80080
	global_load_lds_dwordx4 v[2:3], off
	v_lshl_add_u64 v[2:3], v[204:205], 0, s[16:17]
	s_mov_b32 m0, s71
	s_addc_u32 s57, s57, 0
	global_load_lds_dwordx4 v[2:3], off
	v_lshl_add_u64 v[2:3], s[56:57], 0, v[198:199]
	s_add_i32 m0, s48, 0x20000
	s_and_b64 vcc, exec, s[2:3]
	v_lshl_add_u64 v[2:3], s[56:57], 0, v[196:197]
	s_add_i32 m0, s48, 0x22000
	s_nop 0
	v_lshl_add_u64 v[2:3], v[206:207], 0, s[16:17]
	s_add_i32 m0, s48, 0xc000
	s_nop 0
	global_load_lds_dwordx4 v[2:3], off
	v_lshl_add_u64 v[2:3], v[208:209], 0, s[16:17]
	s_add_i32 m0, s48, 0xe000
	s_nop 0
	global_load_lds_dwordx4 v[2:3], off
	s_add_u32 s34, s34, 0x100
	s_addc_u32 s35, s35, 0
	s_add_u32 s18, s18, 0x100
	s_addc_u32 s41, s41, 0
	s_branch .Lq5_top
	s_nop 0
	s_nop 0
	s_nop 0
	s_nop 0

.LBB0_1281:
	s_cmp_lt_i32 s79, 1
	s_cselect_b64 s[34:35], -1, 0
	s_add_u32 s38, s38, 0x80080
	s_addc_u32 s39, s39, 0
	v_mov_b32_e32 v2, v0
	v_mov_b32_e32 v3, v0
	s_add_u32 s16, s4, 0x100
	v_mov_b32_e32 v1, v0
	v_mov_b32_e32 v112, 0
	v_mov_b64_e32 v[6:7], v[2:3]
	v_mov_b64_e32 v[10:11], v[2:3]
	v_mov_b64_e32 v[22:23], v[2:3]
	v_mov_b64_e32 v[26:27], v[2:3]
	v_mov_b64_e32 v[38:39], v[2:3]
	v_mov_b64_e32 v[42:43], v[2:3]
	v_mov_b64_e32 v[54:55], v[2:3]
	v_mov_b64_e32 v[58:59], v[2:3]
	v_mov_b64_e32 v[14:15], v[2:3]
	v_mov_b64_e32 v[18:19], v[2:3]
	v_mov_b64_e32 v[30:31], v[2:3]
	v_mov_b64_e32 v[34:35], v[2:3]
	v_mov_b64_e32 v[46:47], v[2:3]
	v_mov_b64_e32 v[50:51], v[2:3]
	v_mov_b64_e32 v[62:63], v[2:3]
	v_mov_b64_e32 v[66:67], v[2:3]
	v_mov_b64_e32 v[90:91], v[2:3]
	v_mov_b64_e32 v[106:107], v[2:3]
	v_mov_b64_e32 v[110:111], v[2:3]
	v_mov_b64_e32 v[118:119], v[2:3]
	v_mov_b64_e32 v[126:127], v[2:3]
	v_mov_b64_e32 v[130:131], v[2:3]
	v_mov_b64_e32 v[142:143], v[2:3]
	v_mov_b64_e32 v[146:147], v[2:3]
	s_addc_u32 s27, s5, 0
	s_mov_b32 s84, -2
	v_cndmask_b32_e64 v251, 0, 1, s[34:35]
	v_mov_b64_e32 v[4:5], v[0:1]
	v_mov_b64_e32 v[8:9], v[0:1]
	v_mov_b64_e32 v[20:21], v[0:1]
	v_mov_b64_e32 v[24:25], v[0:1]
	v_mov_b64_e32 v[36:37], v[0:1]
	v_mov_b64_e32 v[40:41], v[0:1]
	v_mov_b64_e32 v[52:53], v[0:1]
	v_mov_b64_e32 v[56:57], v[0:1]
	v_mov_b64_e32 v[12:13], v[0:1]
	v_mov_b64_e32 v[16:17], v[0:1]
	v_mov_b64_e32 v[28:29], v[0:1]
	v_mov_b64_e32 v[32:33], v[0:1]
	v_mov_b64_e32 v[44:45], v[0:1]
	v_mov_b64_e32 v[48:49], v[0:1]
	v_mov_b64_e32 v[60:61], v[0:1]
	v_mov_b64_e32 v[64:65], v[0:1]
	v_mov_b64_e32 v[88:89], v[0:1]
	v_mov_b64_e32 v[104:105], v[0:1]
	v_mov_b64_e32 v[108:109], v[0:1]
	v_mov_b64_e32 v[116:117], v[0:1]
	v_mov_b64_e32 v[124:125], v[0:1]
	v_mov_b64_e32 v[128:129], v[0:1]
	v_mov_b64_e32 v[140:141], v[0:1]
	v_mov_b64_e32 v[144:145], v[0:1]
	v_mov_b32_e32 v113, v112
	v_mov_b32_e32 v114, v112
	v_mov_b32_e32 v115, v112
	v_mov_b32_e32 v120, v112
	v_mov_b32_e32 v121, v112
	v_mov_b32_e32 v122, v112
	v_mov_b32_e32 v123, v112
	v_mov_b32_e32 v132, v112
	v_mov_b32_e32 v133, v112
	v_mov_b32_e32 v134, v112
	v_mov_b32_e32 v135, v112
	v_mov_b32_e32 v136, v112
	v_mov_b32_e32 v137, v112
	v_mov_b32_e32 v138, v112
	v_mov_b32_e32 v139, v112
	v_mov_b32_e32 v148, v112
	v_mov_b32_e32 v149, v112
	v_mov_b32_e32 v150, v112
	v_mov_b32_e32 v151, v112
	v_mov_b32_e32 v152, v112
	v_mov_b32_e32 v153, v112
	v_mov_b32_e32 v154, v112
	v_mov_b32_e32 v155, v112
	v_mov_b32_e32 v156, v112
	v_mov_b32_e32 v157, v112
	v_mov_b32_e32 v158, v112
	v_mov_b32_e32 v159, v112
	v_mov_b32_e32 v160, v112
	v_mov_b32_e32 v161, v112
	v_mov_b32_e32 v162, v112
	v_mov_b32_e32 v163, v112
	s_andn2_b64 vcc, exec, s[34:35]
	s_cbranch_vccnz .Lq6_entry
	s_branch .LBB0_1283
	s_nop 0
	s_nop 0
	s_nop 0
	s_nop 0
	s_nop 0
	s_nop 0
	s_nop 0
	s_nop 0
	s_nop 0

.LBB0_1283:
	ds_read_b128 v[180:183], v247
	ds_read_b128 v[184:187], v247 offset:1024
	ds_read_b128 v[188:191], v247 offset:2048
	ds_read_b128 v[192:195], v247 offset:3072
	ds_read_b128 v[164:167], v248
	ds_read_b128 v[168:171], v248 offset:1024
	ds_read_b128 v[172:175], v248 offset:2048
	ds_read_b128 v[176:179], v248 offset:3072
	v_lshl_add_u64 v[2:3], s[38:39], 0, v[232:233]
	s_add_i32 m0, s44, 0xc000
	ds_read_b128 v[220:223], v249
	ds_read_b128 v[224:227], v249 offset:1024
	ds_read_b128 v[212:215], v249 offset:2048
	ds_read_b128 v[216:219], v249 offset:3072
	ds_read_b128 v[204:207], v249 offset:4096
	ds_read_b128 v[208:211], v249 offset:5120
	ds_read_b128 v[196:199], v249 offset:6144
	ds_read_b128 v[200:203], v249 offset:7168
	global_load_lds_dwordx4 v[2:3], off
	v_lshl_add_u64 v[2:3], s[38:39], 0, v[234:235]
	s_add_i32 m0, s44, 0xe000
	s_nop 0
	global_load_lds_dwordx4 v[2:3], off
	s_waitcnt vmcnt(8)
	s_waitcnt lgkmcnt(0)
	s_barrier
	s_setprio 1
	s_waitcnt lgkmcnt(0)
	v_mfma_f32_16x16x32_bf16 v[68:71], v[180:183], v[220:223], v[160:163]
	v_mfma_f32_16x16x32_bf16 v[72:75], v[188:191], v[220:223], v[156:159]
	v_mfma_f32_16x16x32_bf16 v[76:79], v[180:183], v[212:215], v[152:155]
	v_mfma_f32_16x16x32_bf16 v[80:83], v[188:191], v[212:215], v[148:151]
	v_mfma_f32_16x16x32_bf16 v[84:87], v[180:183], v[204:207], v[136:139]
	v_mfma_f32_16x16x32_bf16 v[92:95], v[188:191], v[204:207], v[132:135]
	v_mfma_f32_16x16x32_bf16 v[96:99], v[180:183], v[196:199], v[120:123]
	v_mfma_f32_16x16x32_bf16 v[100:103], v[188:191], v[196:199], v[112:115]
	v_mfma_f32_16x16x32_bf16 v[68:71], v[184:187], v[224:227], v[68:71]
	v_mfma_f32_16x16x32_bf16 v[72:75], v[192:195], v[224:227], v[72:75]
	v_mfma_f32_16x16x32_bf16 v[76:79], v[184:187], v[216:219], v[76:79]
	v_mfma_f32_16x16x32_bf16 v[80:83], v[192:195], v[216:219], v[80:83]
	v_mfma_f32_16x16x32_bf16 v[84:87], v[184:187], v[208:211], v[84:87]
	v_mfma_f32_16x16x32_bf16 v[92:95], v[192:195], v[208:211], v[92:95]
	v_mfma_f32_16x16x32_bf16 v[96:99], v[184:187], v[200:203], v[96:99]
	v_mfma_f32_16x16x32_bf16 v[100:103], v[192:195], v[200:203], v[100:103]
	s_setprio 0
	v_cmp_ne_u32_e64 s[4:5], 1, v251
	s_andn2_b64 vcc, exec, s[34:35]
	s_setprio 1
	v_mfma_f32_16x16x32_bf16 v[112:115], v[164:167], v[220:223], v[144:147]
	v_mfma_f32_16x16x32_bf16 v[144:147], v[168:171], v[224:227], v[112:115]
	v_mfma_f32_16x16x32_bf16 v[112:115], v[172:175], v[220:223], v[140:143]
	v_mfma_f32_16x16x32_bf16 v[140:143], v[176:179], v[224:227], v[112:115]
	v_mfma_f32_16x16x32_bf16 v[112:115], v[164:167], v[212:215], v[128:131]
	v_mfma_f32_16x16x32_bf16 v[128:131], v[168:171], v[216:219], v[112:115]
	v_mfma_f32_16x16x32_bf16 v[112:115], v[172:175], v[212:215], v[124:127]
	v_mfma_f32_16x16x32_bf16 v[124:127], v[176:179], v[216:219], v[112:115]
	v_mfma_f32_16x16x32_bf16 v[112:115], v[164:167], v[204:207], v[116:119]
	v_mfma_f32_16x16x32_bf16 v[108:111], v[172:175], v[204:207], v[108:111]
	v_mfma_f32_16x16x32_bf16 v[104:107], v[164:167], v[196:199], v[104:107]
	v_mfma_f32_16x16x32_bf16 v[88:91], v[172:175], v[196:199], v[88:91]
	v_mfma_f32_16x16x32_bf16 v[116:119], v[168:171], v[208:211], v[112:115]
	v_mfma_f32_16x16x32_bf16 v[108:111], v[176:179], v[208:211], v[108:111]
	v_mfma_f32_16x16x32_bf16 v[104:107], v[168:171], v[200:203], v[104:107]
	v_mfma_f32_16x16x32_bf16 v[88:91], v[176:179], v[200:203], v[88:91]
	s_setprio 0

.Lq6_entry:
	v_mov_b32_e32 v4, 0
	v_mov_b32_e32 v5, 0
	v_mov_b32_e32 v6, 0
	v_mov_b32_e32 v7, 0
	v_mov_b32_e32 v8, 0
	v_mov_b32_e32 v9, 0
	v_mov_b32_e32 v10, 0
	v_mov_b32_e32 v11, 0
	v_mov_b32_e32 v12, 0
	v_mov_b32_e32 v13, 0
	v_mov_b32_e32 v14, 0
	v_mov_b32_e32 v15, 0
	v_mov_b32_e32 v16, 0
	v_mov_b32_e32 v17, 0
	v_mov_b32_e32 v18, 0
	v_mov_b32_e32 v19, 0
	v_mov_b32_e32 v20, 0
	v_mov_b32_e32 v21, 0
	v_mov_b32_e32 v22, 0
	v_mov_b32_e32 v23, 0
	v_mov_b32_e32 v24, 0
	v_mov_b32_e32 v25, 0
	v_mov_b32_e32 v26, 0
	v_mov_b32_e32 v27, 0
	v_mov_b32_e32 v28, 0
	v_mov_b32_e32 v29, 0
	v_mov_b32_e32 v30, 0
	v_mov_b32_e32 v31, 0
	v_mov_b32_e32 v32, 0
	v_mov_b32_e32 v33, 0
	v_mov_b32_e32 v34, 0
	v_mov_b32_e32 v35, 0
	v_mov_b32_e32 v36, 0
	v_mov_b32_e32 v37, 0
	v_mov_b32_e32 v38, 0
	v_mov_b32_e32 v39, 0
	v_mov_b32_e32 v40, 0
	v_mov_b32_e32 v41, 0
	v_mov_b32_e32 v42, 0
	v_mov_b32_e32 v43, 0
	v_mov_b32_e32 v44, 0
	v_mov_b32_e32 v45, 0
	v_mov_b32_e32 v46, 0
	v_mov_b32_e32 v47, 0
	v_mov_b32_e32 v48, 0
	v_mov_b32_e32 v49, 0
	v_mov_b32_e32 v50, 0
	v_mov_b32_e32 v51, 0
	v_cmp_ne_u32_e64 s[4:5], 1, v251
	s_andn2_b64 vcc, exec, s[34:35]
	s_add_u32 s40, s38, 0xfff80080
	s_addc_u32 s41, s39, -1
	s_cmp_eq_u32 s84, 28
	s_cselect_b32 s47, s29, s41
	s_cselect_b32 s46, s28, s40
	s_cselect_b32 s41, s37, s27
	s_cselect_b32 s40, s36, s16
	s_mov_b32 m0, s49
	v_lshl_add_u64 v[2:3], s[40:41], 0, v[230:231]
	s_add_u32 s86, s40, 0x80000
	global_load_lds_dwordx4 v[2:3], off
	v_lshl_add_u64 v[236:237], s[40:41], 0, v[228:229]
	s_mov_b32 m0, s50
	s_addc_u32 s87, s41, 0
	global_load_lds_dwordx4 v[236:237], off
	v_lshl_add_u64 v[54:55], s[86:87], 0, v[230:231]
	s_mov_b32 m0, s61
	v_lshl_add_u64 v[238:239], s[46:47], 0, v[230:231]
	v_lshl_add_u64 v[54:55], s[86:87], 0, v[228:229]
	s_mov_b32 m0, s62
	v_lshl_add_u64 v[240:241], s[46:47], 0, v[228:229]
	s_mov_b32 m0, s56
	s_and_b64 vcc, exec, s[4:5]
	global_load_lds_dwordx4 v[238:239], off
	s_mov_b32 m0, s57
	s_nop 0
	global_load_lds_dwordx4 v[240:241], off
	s_and_b64 vcc, exec, s[4:5]
	s_mov_b32 m0, s65
	v_lshl_add_u64 v[2:3], v[2:3], 0, s[14:15]
	s_add_u32 s40, s40, 0x80080
	global_load_lds_dwordx4 v[2:3], off
	v_lshl_add_u64 v[2:3], v[236:237], 0, s[14:15]
	s_mov_b32 m0, s66
	s_addc_u32 s41, s41, 0
	global_load_lds_dwordx4 v[2:3], off
	v_lshl_add_u64 v[2:3], s[40:41], 0, v[230:231]
	s_add_i32 m0, s44, 0x20000
	s_and_b64 vcc, exec, s[4:5]
	v_lshl_add_u64 v[2:3], s[40:41], 0, v[228:229]
	s_add_i32 m0, s44, 0x22000
	s_nop 0
	v_lshl_add_u64 v[2:3], v[238:239], 0, s[14:15]
	s_add_i32 m0, s44, 0xc000
	s_nop 0
	global_load_lds_dwordx4 v[2:3], off
	v_lshl_add_u64 v[2:3], v[240:241], 0, s[14:15]
	s_add_i32 m0, s44, 0xe000
	s_nop 0
	global_load_lds_dwordx4 v[2:3], off
	s_add_u32 s38, s38, 0x100
	s_addc_u32 s39, s39, 0
	s_add_u32 s16, s16, 0x100
	s_addc_u32 s27, s27, 0
	s_branch .Lq6_top
	s_nop 0
	s_nop 0
	s_nop 0
	s_nop 0
	s_nop 0
	s_nop 0
	s_nop 0
